# score tile tails: mask compares moved into the MFMA-to-VALU wait window with SGPR-pair results (no compare/nop pairs on the tail chain), on top of v6
# baseline (speedup 1.0000x reference)
; #define LAS __attribute__((address_space(3)))
; __device__ __forceinline__ void retention_fused(const Params& p, LAS unsigned char* lds, int unit) {
;     ...
;                 for (int t = 0; t < 2; ++t) { const int jt = 2 * a + t;
;                     sc[t] = (f32x4){0.f, 0.f, 0.f, 0.f};
;                     if (jt <= wid) {
; #pragma unroll
;                         for (int ks = 0; ks < 8; ++ks) { const bf16x8 kf = *(const LAS bf16x8*)(Ks + (jt * 16 + fr) * KS_STRIDE + ks * 64 + fq * 16);
;                             sc[t] = __builtin_amdgcn_mfma_f32_16x16x32_bf16(kf, qf[ks], sc[t], 0, 0, 0); }
;                         const float tf = __builtin_amdgcn_exp2f((float)(16 * (wid - jt)) * log2g);
; #pragma unroll
;                         for (int r = 0; r < 4; ++r) { const int dij = 16 * (wid - jt) + fr - fq * 4 - r;
;                             sc[t][r] = dij >= 0 ? sc[t][r] * (tf * __builtin_amdgcn_exp2f((float)(fr - fq * 4 - r) * log2g)) : 0.f; }
;                     } }
.LBB0_1047:
	ds_read_b128 v[230:233], v224 offset:8576
	ds_read_b128 v[234:237], v224 offset:8640
	ds_read_b128 v[238:241], v224 offset:8704
	ds_read_b128 v[242:245], v224 offset:8768
	v_add_u32_e32 v246, -16, v225
	s_add_i32 s28, s27, -16
	s_waitcnt lgkmcnt(5)
	v_mfma_f32_16x16x32_bf16 v[226:229], v[248:251], v[82:85], 0
	s_waitcnt lgkmcnt(4)
	v_mfma_f32_16x16x32_bf16 v[226:229], v[252:255], v[86:89], v[226:229]
	s_waitcnt lgkmcnt(3)
	v_mfma_f32_16x16x32_bf16 v[226:229], v[230:233], v[90:93], v[226:229]
	ds_read_b128 v[230:233], v224 offset:8832
	s_waitcnt lgkmcnt(3)
	v_mfma_f32_16x16x32_bf16 v[226:229], v[234:237], v[94:97], v[226:229]
	ds_read_b128 v[234:237], v224 offset:8896
	s_waitcnt lgkmcnt(3)
	v_mfma_f32_16x16x32_bf16 v[224:227], v[238:241], v[98:101], v[226:229]
	v_sub_u32_e32 v238, v246, v130
	v_sub_u32_e32 v239, v246, v1
	v_cmp_lt_i32_e32 vcc, -1, v238
	s_waitcnt lgkmcnt(2)
	v_mfma_f32_16x16x32_bf16 v[224:227], v[242:245], v[102:105], v[224:227]
	v_cvt_f32_i32_e32 v228, s28
	v_sub_u32_e32 v240, v246, v152
	v_mul_f32_e32 v228, v153, v228
	s_waitcnt lgkmcnt(1)
	v_mfma_f32_16x16x32_bf16 v[224:227], v[230:233], v[106:109], v[224:227]
	v_exp_f32_e32 v228, v228
	v_sub_u32_e32 v232, v246, v115
	v_pk_mul_f32 v[230:231], v[150:151], v[228:229] op_sel_hi:[1,0]
	s_waitcnt lgkmcnt(0)
	v_mfma_f32_16x16x32_bf16 v[224:227], v[234:237], v[110:113], v[224:227]
	ds_read_b128 v[248:251], v163 offset:16896
	ds_read_b128 v[252:255], v163 offset:16960
	v_pk_mul_f32 v[228:229], v[154:155], v[228:229] op_sel_hi:[1,0]
	v_cmp_lt_i32_e64 s[98:99], -1, v239
	v_cmp_lt_i32_e64 s[100:101], -1, v240
	s_nop 2
	v_pk_mul_f32 v[224:225], v[230:231], v[224:225]
	v_pk_mul_f32 v[228:229], v[228:229], v[226:227]
	v_cndmask_b32_e32 v226, 0, v224, vcc
	v_cmp_lt_i32_e32 vcc, -1, v232
	v_cndmask_b32_e64 v224, 0, v225, s[98:99]
	v_cndmask_b32_e64 v225, 0, v228, s[100:101]
	v_cndmask_b32_e32 v227, 0, v229, vcc

; #define LAS __attribute__((address_space(3)))
; __device__ __forceinline__ void retention_fused(const Params& p, LAS unsigned char* lds, int unit) {
;     ...
;                 for (int t = 0; t < 2; ++t) { const int jt = 2 * a + t;
;                     sc[t] = (f32x4){0.f, 0.f, 0.f, 0.f};
;                     if (jt <= wid) {
; #pragma unroll
;                         for (int ks = 0; ks < 8; ++ks) { const bf16x8 kf = *(const LAS bf16x8*)(Ks + (jt * 16 + fr) * KS_STRIDE + ks * 64 + fq * 16);
;                             sc[t] = __builtin_amdgcn_mfma_f32_16x16x32_bf16(kf, qf[ks], sc[t], 0, 0, 0); }
;                         const float tf = __builtin_amdgcn_exp2f((float)(16 * (wid - jt)) * log2g);
; #pragma unroll
;                         for (int r = 0; r < 4; ++r) { const int dij = 16 * (wid - jt) + fr - fq * 4 - r;
;                             sc[t][r] = dij >= 0 ? sc[t][r] * (tf * __builtin_amdgcn_exp2f((float)(fr - fq * 4 - r) * log2g)) : 0.f; }
;                     } }
.LBB0_1049:
	v_add_u32_e32 v224, 0, v163
	ds_read_b128 v[230:233], v224 offset:128
	ds_read_b128 v[234:237], v224 offset:192
	ds_read_b128 v[238:241], v224 offset:256
	ds_read_b128 v[242:245], v224 offset:320
	v_cvt_f32_i32_e32 v179, s27
	v_add_u32_e32 v225, s27, v114
	s_waitcnt lgkmcnt(5)
	v_mfma_f32_16x16x32_bf16 v[226:229], v[248:251], v[82:85], 0
	v_sub_u32_e32 v221, v225, v1
	v_mul_f32_e32 v179, v153, v179
	v_exp_f32_e32 v222, v179
	s_waitcnt lgkmcnt(4)
	v_mfma_f32_16x16x32_bf16 v[226:229], v[252:255], v[86:89], v[226:229]
	v_sub_u32_e32 v246, v225, v130
	v_cmp_lt_i32_e32 vcc, -1, v221
	s_waitcnt lgkmcnt(3)
	v_mfma_f32_16x16x32_bf16 v[226:229], v[230:233], v[90:93], v[226:229]
	ds_read_b128 v[230:233], v224 offset:384
	s_cmp_lt_u32 s26, s17
	s_waitcnt lgkmcnt(3)
	v_mfma_f32_16x16x32_bf16 v[226:229], v[234:237], v[94:97], v[226:229]
	ds_read_b128 v[234:237], v224 offset:448
	s_waitcnt lgkmcnt(3)
	v_mfma_f32_16x16x32_bf16 v[226:229], v[238:241], v[98:101], v[226:229]
	s_waitcnt lgkmcnt(2)
	v_mfma_f32_16x16x32_bf16 v[226:229], v[242:245], v[102:105], v[226:229]
	v_sub_u32_e32 v238, v225, v115
	s_waitcnt lgkmcnt(1)
	v_mfma_f32_16x16x32_bf16 v[226:229], v[230:233], v[106:109], v[226:229]
	v_mul_f32_e64 v230, v150, v222
	v_mul_f32_e64 v231, v151, v222
	v_pk_mul_f32 v[222:223], v[154:155], v[222:223] op_sel_hi:[1,0]
	v_sub_u32_e32 v232, v225, v152
	s_waitcnt lgkmcnt(0)
	v_mfma_f32_16x16x32_bf16 v[226:229], v[234:237], v[110:113], v[226:229]
	ds_read_b128 v[248:251], v224 offset:8448
	ds_read_b128 v[252:255], v224 offset:8512
	v_cmp_lt_i32_e64 s[98:99], -1, v246
	v_cmp_lt_i32_e64 s[100:101], -1, v238
	s_nop 3
	v_pk_mul_f32 v[226:227], v[230:231], v[226:227]
	v_pk_mul_f32 v[228:229], v[222:223], v[228:229]
	v_cndmask_b32_e32 v179, 0, v227, vcc
	v_cmp_lt_i32_e32 vcc, -1, v232
	v_cndmask_b32_e64 v221, 0, v226, s[98:99]
	v_cndmask_b32_e64 v222, 0, v229, s[100:101]
	v_mov_b32_e32 v226, 0
	v_cndmask_b32_e32 v223, 0, v228, vcc
	s_cbranch_scc1 .LBB0_1047
	v_mov_b32_e32 v224, 0
	v_mov_b32_e32 v225, 0
	v_mov_b32_e32 v227, 0
	s_branch .LBB0_1048

; __global__ void __launch_bounds__(NTHREADS, 2) mega_fwd(Params p) {
	.amdhsa_kernel _Z8mega_fwd6Params
		.amdhsa_group_segment_fixed_size 0
		.amdhsa_private_segment_fixed_size 0
		.amdhsa_kernarg_size 408
		.amdhsa_user_sgpr_count 2
		.amdhsa_user_sgpr_dispatch_ptr 0
		.amdhsa_user_sgpr_queue_ptr 0
		.amdhsa_user_sgpr_kernarg_segment_ptr 1
		.amdhsa_user_sgpr_dispatch_id 0
		.amdhsa_user_sgpr_kernarg_preload_length 0
		.amdhsa_user_sgpr_kernarg_preload_offset 0
		.amdhsa_user_sgpr_private_segment_size 0
		.amdhsa_uses_dynamic_stack 0
		.amdhsa_enable_private_segment 0
		.amdhsa_system_sgpr_workgroup_id_x 1
		.amdhsa_system_sgpr_workgroup_id_y 0
		.amdhsa_system_sgpr_workgroup_id_z 0
		.amdhsa_system_sgpr_workgroup_info 0
		.amdhsa_system_vgpr_workitem_id 2
		.amdhsa_next_free_vgpr 256
		.amdhsa_next_free_sgpr 102
		.amdhsa_accum_offset 256
		.amdhsa_reserve_vcc 1
		.amdhsa_float_round_mode_32 0
		.amdhsa_float_round_mode_16_64 0
		.amdhsa_float_denorm_mode_32 3
		.amdhsa_float_denorm_mode_16_64 3
		.amdhsa_dx10_clamp 1
		.amdhsa_ieee_mode 1
		.amdhsa_fp16_overflow 0
		.amdhsa_tg_split 0
		.amdhsa_exception_fp_ieee_invalid_op 0
		.amdhsa_exception_fp_denorm_src 0
		.amdhsa_exception_fp_ieee_div_zero 0
		.amdhsa_exception_fp_ieee_overflow 0
		.amdhsa_exception_fp_ieee_underflow 0
		.amdhsa_exception_fp_ieee_inexact 0
		.amdhsa_exception_int_div_zero 0
	.end_amdhsa_kernel

; __global__ void __launch_bounds__(NTHREADS, 2) mega_fwd(Params p) {
.Lfunc_end0:
	.size	_Z8mega_fwd6Params, .Lfunc_end0-_Z8mega_fwd6Params
	.set _Z8mega_fwd6Params.num_vgpr, 256
	.set _Z8mega_fwd6Params.num_agpr, 0
	.set _Z8mega_fwd6Params.numbered_sgpr, 102
	.set _Z8mega_fwd6Params.num_named_barrier, 0
	.set _Z8mega_fwd6Params.private_seg_size, 0
	.set _Z8mega_fwd6Params.uses_vcc, 1
	.set _Z8mega_fwd6Params.uses_flat_scratch, 0
	.set _Z8mega_fwd6Params.has_dyn_sized_stack, 0
	.set _Z8mega_fwd6Params.has_recursion, 0
	.set _Z8mega_fwd6Params.has_indirect_call, 0

; __global__ void __launch_bounds__(NTHREADS, 2) mega_fwd(Params p) {
amdhsa.kernels:
  - .agpr_count:     0
    .args:
      - .offset:         0
        .size:           152
        .value_kind:     by_value
      - .offset:         152
        .size:           4
        .value_kind:     hidden_block_count_x
      - .offset:         156
        .size:           4
        .value_kind:     hidden_block_count_y
      - .offset:         160
        .size:           4
        .value_kind:     hidden_block_count_z
      - .offset:         164
        .size:           2
        .value_kind:     hidden_group_size_x
      - .offset:         166
        .size:           2
        .value_kind:     hidden_group_size_y
      - .offset:         168
        .size:           2
        .value_kind:     hidden_group_size_z
      - .offset:         170
        .size:           2
        .value_kind:     hidden_remainder_x
      - .offset:         172
        .size:           2
        .value_kind:     hidden_remainder_y
      - .offset:         174
        .size:           2
        .value_kind:     hidden_remainder_z
      - .offset:         192
        .size:           8
        .value_kind:     hidden_global_offset_x
      - .offset:         200
        .size:           8
        .value_kind:     hidden_global_offset_y
      - .offset:         208
        .size:           8
        .value_kind:     hidden_global_offset_z
      - .offset:         216
        .size:           2
        .value_kind:     hidden_grid_dims
      - .offset:         240
        .size:           8
        .value_kind:     hidden_multigrid_sync_arg
      - .offset:         272
        .size:           4
        .value_kind:     hidden_dynamic_lds_size
    .group_segment_fixed_size: 0
    .kernarg_segment_align: 8
    .kernarg_segment_size: 408
    .language:       OpenCL C
    .language_version:
      - 2
      - 0
    .max_flat_workgroup_size: 512
    .name:           _Z8mega_fwd6Params
    .private_segment_fixed_size: 0
    .sgpr_count:     108
    .sgpr_spill_count: 63
    .symbol:         _Z8mega_fwd6Params.kd
    .uniform_work_group_size: 1
    .uses_dynamic_stack: false
    .vgpr_count:     256
    .vgpr_spill_count: 0
    .wavefront_size: 64
